# unit prologues: A bias table built with all loads in flight and one wait, B bias loads merged into the tile DMA wait; unit-boundary barriers no longer drain output stores
# baseline (speedup 1.0000x reference)
; #define ATT_WAIT_BAR() asm volatile("s_waitcnt vmcnt(0) lgkmcnt(0)\n\ts_barrier" ::: "memory")
; DI void attn_phase(const Params& P, char* shm) {
;     ...
;             if (tid == 0) su[0] = atomicAdd(cnt, 1u);
;             ATT_WAIT_BAR();
;             const unsigned ui = su[0];
;             ATT_WAIT_BAR();
;             if (ui >= 384u) break;
;             const unsigned e = P.order[q * 384 + ui]; const int kind = e >> 28, b = (e >> 24) & 15, h = (e >> 16) & 255, qb = e & 0xffff;
;     ...
;             { const int reps = (kind == 0) ? PROBE_REP_A : (kind == 2 ? PROBE_REP_C : 1);
;               for (int rep = 1; rep < reps; ++rep) { if (kind == 0) attn_unit<0>(P, b, h, qb, shm, lam, P.lam_init > -1.0f); else attn_unit<2>(P, b, h, qb, shm, lam, P.lam_init > -1.0f); ATT_WAIT_BAR(); } }
;     ...
;             if (kind == 0) attn_unit<0>(P, b, h, qb, shm, lam);
;             else if (kind == 1) attn_unit<1>(P, b, h, qb, shm, lam);
;             else attn_unit<2>(P, b, h, qb, shm, lam);
;             ATT_WAIT_BAR();
.LBB0_317:
	s_waitcnt lgkmcnt(0)
	s_barrier
.LBB0_318:
	s_waitcnt lgkmcnt(0)
	s_barrier
	s_mov_b64 s[0:1], 0

; #define LAS __attribute__((address_space(3)))
; template <int KIND> DI void attn_unit(const Params& P, int b, int h, int qb, char* shm, float lam, bool dry = false) {
;     ...
;     if (KIND == 0) { qrow0 = qb * 128 + 32 * (wid & 3); qoff = h * 128 + m * 64; T_lo = 0; T_hi = 2 * qb + 1; wt_lo = 0; wt_hi = 2 * qb + ((wid & 3) >> 1); }
;     else if (KIND == 1) { qrow0 = qb * 256 + 32 * wid; qoff = 512 + h * 64; const int cq = 4 * qb + (wid >> 1); T_lo = 4 * qb - 8 < 0 ? 0 : 4 * qb - 8; T_hi = 4 * qb + 3; wt_lo = cq - 8 < 0 ? 0 : cq - 8; wt_hi = cq; }
;     else { qrow0 = qb * 256 + 32 * wid; qoff = 1024 + h * 64; T_lo = 0; T_hi = 4 * qb + 3; wt_lo = 0; wt_hi = 4 * qb + (wid >> 1); }
;     const int kvoff = (KIND == 0) ? h * 128 : qoff;
;     const unsigned lds0 = (unsigned)(uintptr_t)shm;
;     const lds_cptr shm3 = (lds_cptr)shm;
;     const int hk = kvoff >> 6, vb0 = kvoff >> 5;
;     const bf16_t* ksrc = P.Kp + ((size_t)(b * 24 + hk) * 256) * 4096 + wid * 512 + lane * 8;
;     const bf16_t* vsrc0 = P.Vp + ((size_t)(b * 48 + vb0 + (wid >> 2)) * 256) * 2048 + (wid & 3) * 512 + lane * 8;
;     const bf16_t* kxsrc = P.KX + ((size_t)(b * 8 + h) * SEQ + lane) * 8;
;     ...
;     float cb = 0.f;
;     if (KIND == 0) { cb = P.t5[15 * 4 + h] * LOG2E;
;         for (int i = tid; i < 2175; i += 512) { const int rel = i - 2111; const int n = rel < 0 ? -rel : rel;
;             int lg = 36 - __builtin_clz((unsigned)(n | 1)); lg = lg > 15 ? 15 : lg; int idx = n < 8 ? n : lg; idx += rel > 0 ? 16 : 0;
;             *(LAS float*)(shm3 + OFF_TAB + i * 4) = P.t5[idx * 4 + h] * LOG2E - cb; } }
;     if (KIND == 1) { cb = P.relb[h] * LOG2E;
;         if (tid < 255) { int idx = tid - 191; idx = idx < -128 ? -128 : idx; *(LAS float*)(shm3 + OFF_TAB + tid * 4) = P.relb[(idx + 128) * 8 + h] * LOG2E - cb; } }
;     const int NT = T_hi - T_lo + 1;
;     ...
;     ATT_DMA(ATT_TILE(0), 0);
;     if (NT > 1) ATT_DMA(ATT_TILE(1), SLOT);
;     if (NT > 2) ATT_DMA(ATT_TILE(2), 2 * SLOT);
; DI void attn_phase(const Params& P, char* shm) {
;     ...
;             if (tid == 0) su[0] = atomicAdd(cnt, 1u);
;             ATT_WAIT_BAR();
;             const unsigned ui = su[0];
;             ATT_WAIT_BAR();
;             if (ui >= 384u) break;
;             const unsigned e = P.order[q * 384 + ui]; const int kind = e >> 28, b = (e >> 24) & 15, h = (e >> 16) & 255, qb = e & 0xffff;
.LBB0_324:
	s_or_b64 exec, exec, s[0:1]
	s_waitcnt lgkmcnt(0)
	s_barrier
	v_mov_b32_e32 v0, s87
	ds_read_b32 v0, v0
	s_waitcnt lgkmcnt(0)
	s_barrier
	s_movk_i32 s0, 0x17f
	s_waitcnt lgkmcnt(0)
	v_cmp_lt_u32_e32 vcc, s0, v0
	s_mov_b64 s[0:1], -1
	s_cbranch_vccnz .LBB0_319
	v_add_u32_e32 v0, s41, v0
	v_mov_b32_e32 v1, v2
	v_lshlrev_b64 v[0:1], 2, v[0:1]
	v_lshl_add_u64 v[0:1], s[22:23], 0, v[0:1]
	global_load_dword v166, v[0:1], off
	s_brev_b32 s1, -16
	s_waitcnt vmcnt(0)
	v_readfirstlane_b32 s0, v166
	v_cmp_lt_u32_e32 vcc, s1, v166
	s_bfe_u32 s2, s0, 0x40018
	s_bfe_u32 s28, s0, 0x80010
	s_and_b32 s3, s0, 0xffff
	s_mov_b64 s[0:1], -1
	s_cbranch_vccz .LBB0_377
	s_brev_b32 s0, -8
	v_cmp_lt_u32_e32 vcc, s0, v166
	s_lshl_b32 s14, s2, 14
	s_lshl_b32 s16, s3, 8
	s_lshl_b32 s15, s28, 6
	s_lshl_b32 s33, s3, 2
	s_mov_b64 s[0:1], -1
	s_mul_i32 s10, s2, 24
	s_cbranch_vccz .LBB0_365
	s_add_i32 s0, s15, 0x400
	v_mov_b32_e32 v53, v236
	s_lshr_b32 s1, s0, 6
	s_add_i32 s1, s1, s10
	v_readfirstlane_b32 s9, v53
	s_ashr_i32 s8, s9, 6
	s_or_b32 s7, s33, 3
	s_lshr_b32 s4, s0, 5
	s_lshl_b32 s0, s1, 21
	s_add_u32 s5, s24, s0
	s_addc_u32 s6, s25, 0
	s_lshl_b32 s0, s8, 9
	s_ashr_i32 s1, s0, 31
	s_lshl_b64 s[0:1], s[0:1], 1
	v_and_b32_e32 v52, 63, v53
	s_add_u32 s0, s5, s0
	s_addc_u32 s1, s6, s1
	v_lshlrev_b32_e32 v0, 4, v52
	v_mov_b32_e32 v1, v2
	v_lshl_add_u64 v[156:157], s[0:1], 0, v[0:1]
	s_mul_i32 s0, s2, 48
	s_add_i32 s0, s4, s0
	s_ashr_i32 s1, s9, 8
	s_add_i32 s0, s0, s1
	s_ashr_i32 s1, s0, 31
	s_lshl_b64 s[0:1], s[0:1], 20
	s_add_u32 s0, s26, s0
	s_addc_u32 s1, s27, s1
	s_lshl_b32 s41, s8, 10
	s_and_b32 s4, s41, 0xc00
	s_add_u32 s0, s0, s4
	s_addc_u32 s1, s1, 0
	s_lshl_b32 s11, s2, 3
	s_add_i32 s11, s11, s28
	s_lshl_b32 s6, s11, 14
	v_lshl_add_u64 v[158:159], s[0:1], 0, v[0:1]
	v_or_b32_e32 v0, s6, v52
	v_readlane_b32 s0, v255, 19
	s_lshl_b32 s20, s7, 13
	v_lshlrev_b32_e32 v0, 4, v0
	v_readlane_b32 s1, v255, 20
	s_cmp_lg_u32 0, -1
	s_nop 0
	v_lshl_add_u64 v[160:161], s[0:1], 0, v[0:1]
	s_cselect_b32 s0, 0, 0
	s_add_i32 s0, s41, s0
	v_lshl_add_u64 v[0:1], v[156:157], 0, s[20:21]
	s_mov_b32 s1, m0
	s_mov_b32 m0, s0
	s_nop 0
	global_load_lds_dwordx4 v[0:1], off
	s_mov_b32 m0, s1
	s_lshl_b32 s20, s7, 12
	s_addk_i32 s0, 0x4000
	s_cmp_lt_u32 s9, 64
	v_lshl_add_u64 v[0:1], v[158:159], 0, s[20:21]
	s_mov_b32 s1, m0
	s_mov_b32 m0, s0
	s_nop 0
	global_load_lds_dwordx4 v[0:1], off
	s_mov_b32 m0, s1
	s_cselect_b64 s[4:5], -1, 0
	s_cmp_gt_u32 s9, 63
	s_cselect_b64 s[0:1], -1, 0
	s_and_b64 vcc, exec, s[0:1]
	s_cbranch_vccnz .LBB0_329
	s_lshl_b32 s20, s7, 10
	s_cmp_lg_u32 0, -1
	s_cselect_b32 s7, 0, 0
	v_lshl_add_u64 v[0:1], v[160:161], 0, s[20:21]
	s_add_i32 s7, s7, 0x8000
	s_mov_b32 s10, m0
	s_mov_b32 m0, s7
	s_nop 0
	global_load_lds_dwordx4 v[0:1], off
	s_mov_b32 m0, s10

; #define LAS __attribute__((address_space(3)))
; template <int KIND> DI void attn_unit(const Params& P, int b, int h, int qb, char* shm, float lam, bool dry = false) {
;     ...
;     if (KIND == 1) { cb = P.relb[h] * LOG2E;
;         if (tid < 255) { int idx = tid - 191; idx = idx < -128 ? -128 : idx; *(LAS float*)(shm3 + OFF_TAB + tid * 4) = P.relb[(idx + 128) * 8 + h] * LOG2E - cb; } }
.LBB0_365:
	s_and_b64 vcc, exec, s[0:1]
	s_cbranch_vccz .LBB0_376
	s_lshl_b32 s0, s28, 2
	v_mov_b32_e32 v0, s0
	v_readlane_b32 s0, v255, 21
	v_mov_b32_e32 v68, v236
	v_readlane_b32 s1, v255, 22
	s_nop 0
	v_readfirstlane_b32 s6, v68
	s_nop 2
	global_load_dword v200, v0, s[0:1]
	s_movk_i32 s0, 0xff
	v_cmp_gt_i32_e32 vcc, s0, v68
	s_and_saveexec_b64 s[0:1], vcc
	s_cbranch_execz .LBB0_368
	v_lshl_add_u32 v0, v68, 2, 0
	v_add_u32_e32 v212, 0x21000, v0
	s_add_i32 s4, s28, 0xfffffe08
	v_max_i32_e32 v0, 63, v68
	v_lshl_add_u32 v0, v0, 3, s4
	v_readlane_b32 s4, v255, 21
	v_mov_b32_e32 v1, v2
	v_readlane_b32 s5, v255, 22
	s_nop 1
	v_lshl_add_u64 v[0:1], v[0:1], 2, s[4:5]
	global_load_dword v201, v[0:1], off

; #define LAS __attribute__((address_space(3)))
; #define ATT_WAIT_BAR() asm volatile("s_waitcnt vmcnt(0) lgkmcnt(0)\n\ts_barrier" ::: "memory")
; template <int KIND> DI void attn_unit(const Params& P, int b, int h, int qb, char* shm, float lam, bool dry = false) {
;     ...
;     if (KIND == 1) { cb = P.relb[h] * LOG2E;
;         if (tid < 255) { int idx = tid - 191; idx = idx < -128 ? -128 : idx; *(LAS float*)(shm3 + OFF_TAB + tid * 4) = P.relb[(idx + 128) * 8 + h] * LOG2E - cb; } }
;     const int NT = T_hi - T_lo + 1;
;     ...
;     ATT_DMA(ATT_TILE(0), 0);
;     if (NT > 1) ATT_DMA(ATT_TILE(1), SLOT);
;     if (NT > 2) ATT_DMA(ATT_TILE(2), 2 * SLOT);
;     bf16x8 qr[4];
;     { const bf16_t* qp = P.Qp + (rowbase + qrow0 + r32) * PITCH + qoff + hi * 8;
; #pragma unroll
;       for (int d0 = 0; d0 < 4; ++d0) qr[d0] = *(const bf16x8*)(qp + d0 * 16); }
;     float qkmax = 0.f;
;     if (KIND == 2) { cb = P.CK[(size_t)(b * 8 + h) * SEQ + qrow0 + r32]; const unsigned* np = P.nrm + (b * 8 + h) * 4; qkmax = (sqrtf(__uint_as_float(np[0]) * __uint_as_float(np[2])) + sqrtf(__uint_as_float(np[1]) * __uint_as_float(np[3]))) * 1.001f + 0.01f; }
;     asm volatile("" : "+v"(qr[0]), "+v"(qr[1]), "+v"(qr[2]), "+v"(qr[3]), "+v"(cb), "+v"(qkmax));
;     bf16x8 ones = (bf16x8){0, 0, 0, 0, 0, 0, 0, 0}; if (KIND == 2 && hi == 0) { ones[0] = 0x3F80; ones[1] = 0x3F80; ones[2] = 0x3F80; }
;     float mhat = 0.f, lsum = 0.f; f32x16 o[NDB]; f32x16 negm;
; #pragma unroll
;     for (int i = 0; i < NDB; ++i) o[i] = f32x16{};
; #pragma unroll
;     for (int r = 0; r < 16; ++r) negm[r] = cb;
;     const int vlane = ((lane >> 4) & 1) * 32 + (lane & 3) * 8 + (4 * hi + ((lane & 15) >> 2)) * 64;
;     LAS unsigned* vote = (LAS unsigned*)(shm3 + OFF_VOTE);
;     if (KIND == 2 && tid < 32) vote[tid] = 0u;
;     ATT_WAIT_BAR();
;     int sc = 0, sd = 3 * SLOT;
;     int nt_eff = NT;
;     ...
;     f32x16 pa0, pa1, pb0, pb1;
;     bf16x8 kf[4], x0, x1;
;     ATT_KLD(0, 0); ATT_XLD(0);
;     pa0 = MF(kf[0], qr[0], negm); pa1 = MF(kf[1], qr[0], negm); pa0 = MF(kf[2], qr[1], pa0); pa1 = MF(kf[3], qr[1], pa1);
;     SBAR(); ATT_KLD(0, 1); SBAR();
;     pa0 = MF(kf[0], qr[2], pa0); pa1 = MF(kf[1], qr[2], pa1); pa0 = MF(kf[2], qr[3], pa0); pa1 = MF(kf[3], qr[3], pa1);
;     if (KIND == 2) { pa0 = MF(x0, ones, pa0); pa1 = MF(x1, ones, pa1); }
;     ATT_FIX(pa0, pa1, ATT_TILE(0));
.LBB0_372:
	s_lshl_b32 s9, s5, 5
	s_add_i32 s9, s9, s16
	s_ashr_i32 s5, s9, 31
	v_and_b32_e32 v146, 31, v68
	s_add_u32 s7, s9, s14
	v_lshrrev_b32_e32 v3, 5, v0
	v_or_b32_e32 v4, s7, v146
	v_mov_b64_e32 v[0:1], s[36:37]
	s_addc_u32 s5, s5, 0
	v_mad_u64_u32 v[0:1], s[10:11], v4, s86, v[0:1]
	v_mad_i32_i24 v1, s5, v242, v1
	s_lshl_b32 s10, s15, 1
	s_mov_b32 s11, s21
	v_lshl_add_u64 v[0:1], v[0:1], 0, s[10:11]
	v_lshlrev_b32_e32 v144, 4, v3
	v_mov_b32_e32 v145, v2
	v_lshl_add_u64 v[152:153], v[0:1], 0, v[144:145]
	global_load_dwordx4 v[116:119], v[152:153], off offset:1120
	global_load_dwordx4 v[120:123], v[152:153], off offset:1088
	global_load_dwordx4 v[124:127], v[152:153], off offset:1056
	global_load_dwordx4 v[128:131], v[152:153], off offset:1024
	v_mov_b32_e32 v0, v2
	v_lshlrev_b32_e32 v1, 10, v3
	v_lshlrev_b32_e32 v4, 4, v146
	v_add3_u32 v158, 0, v1, v4
	v_lshlrev_b32_e32 v145, 2, v3
	s_waitcnt vmcnt(0)
	v_mul_f32_e32 v36, 0x3fb8aa3b, v200
	v_cmp_gt_i32_e32 vcc, 0xff, v236
	s_and_saveexec_b64 vcc, vcc
	v_fma_f32 v201, v201, s60, -v36
	ds_write_b32 v212, v201
	s_mov_b64 exec, vcc
	s_waitcnt vmcnt(0) lgkmcnt(0)
	s_barrier
	ds_read_b128 v[20:23], v158
	ds_read_b128 v[52:55], v158 offset:512
	v_mov_b32_e32 v37, v36
	v_mov_b32_e32 v38, v36
	v_mov_b32_e32 v39, v36
	v_mov_b32_e32 v40, v36
	v_mov_b32_e32 v41, v36
	v_mov_b32_e32 v42, v36
	v_mov_b32_e32 v43, v36
	v_mov_b32_e32 v44, v36
	v_mov_b32_e32 v45, v36
	v_mov_b32_e32 v46, v36
	v_mov_b32_e32 v47, v36
	v_mov_b32_e32 v48, v36
	v_mov_b32_e32 v49, v36
	v_mov_b32_e32 v50, v36
	v_mov_b32_e32 v51, v36
	s_waitcnt lgkmcnt(1)
	s_nop 0
	v_mfma_f32_32x32x16_bf16 v[4:19], v[20:23], v[128:131], v[36:51]
	s_waitcnt lgkmcnt(0)
	v_mfma_f32_32x32x16_bf16 v[20:35], v[52:55], v[128:131], v[36:51]
	ds_read_b128 v[52:55], v158 offset:2048
	s_waitcnt lgkmcnt(0)
	v_mfma_f32_32x32x16_bf16 v[4:19], v[52:55], v[124:127], v[4:19]
	ds_read_b128 v[52:55], v158 offset:2560
	s_waitcnt lgkmcnt(0)
	v_mfma_f32_32x32x16_bf16 v[20:35], v[52:55], v[124:127], v[20:35]
	ds_read_b128 v[52:55], v158 offset:4096
	ds_read_b128 v[56:59], v158 offset:4608
	ds_read_b128 v[60:63], v158 offset:6144
	ds_read_b128 v[64:67], v158 offset:6656
	s_waitcnt lgkmcnt(3)
	v_mfma_f32_32x32x16_bf16 v[4:19], v[52:55], v[120:123], v[4:19]
	s_ashr_i32 s5, s9, 6
	s_add_i32 s5, s5, -2
	s_cmp_lt_i32 s20, s5
	s_waitcnt lgkmcnt(2)
	v_mfma_f32_32x32x16_bf16 v[20:35], v[56:59], v[120:123], v[20:35]
	s_waitcnt lgkmcnt(1)
	v_mfma_f32_32x32x16_bf16 v[4:19], v[60:63], v[116:119], v[4:19]
	s_waitcnt lgkmcnt(0)
	v_mfma_f32_32x32x16_bf16 v[20:35], v[64:67], v[116:119], v[20:35]
	s_cbranch_scc1 .LBB0_374
	v_lshl_or_b32 v0, s20, 6, v145
	v_or_b32_e32 v1, s9, v146
	v_sub_u32_e32 v0, v0, v1
	s_add_i32 s7, 0, 0x21000
	v_lshl_add_u32 v3, v0, 2, s7
	ds_read2_b32 v[0:1], v3 offset0:191 offset1:192
	ds_read2_b32 v[52:53], v3 offset0:193 offset1:194
	ds_read2_b32 v[54:55], v3 offset0:199 offset1:200
	ds_read2_b32 v[56:57], v3 offset0:201 offset1:202
	ds_read2_b32 v[58:59], v3 offset0:207 offset1:208
	ds_read2_b32 v[60:61], v3 offset0:209 offset1:210
	ds_read2_b32 v[62:63], v3 offset0:215 offset1:216
	ds_read2_b32 v[64:65], v3 offset0:217 offset1:218
	ds_read2_b32 v[66:67], v3 offset0:223 offset1:224
	ds_read2_b32 v[70:71], v3 offset0:225 offset1:226
	ds_read2_b32 v[72:73], v3 offset0:231 offset1:232
	ds_read2_b32 v[74:75], v3 offset0:233 offset1:234
	s_waitcnt lgkmcnt(4)
	v_pk_add_f32 v[18:19], v[18:19], v[64:65]
	v_pk_add_f32 v[16:17], v[16:17], v[62:63]
	v_pk_add_f32 v[14:15], v[14:15], v[60:61]
	v_pk_add_f32 v[12:13], v[12:13], v[58:59]
	ds_read2_b32 v[58:59], v3 offset0:239 offset1:240
	ds_read2_b32 v[60:61], v3 offset0:241 offset1:242
	ds_read2_b32 v[62:63], v3 offset0:247 offset1:248
	ds_read2_b32 v[64:65], v3 offset0:249 offset1:250
	v_pk_add_f32 v[10:11], v[10:11], v[56:57]
	v_pk_add_f32 v[8:9], v[8:9], v[54:55]
	v_pk_add_f32 v[6:7], v[6:7], v[52:53]
	v_pk_add_f32 v[4:5], v[4:5], v[0:1]
	s_waitcnt lgkmcnt(0)
	v_pk_add_f32 v[34:35], v[34:35], v[64:65]
	v_pk_add_f32 v[32:33], v[32:33], v[62:63]
	v_pk_add_f32 v[30:31], v[30:31], v[60:61]
	v_pk_add_f32 v[28:29], v[28:29], v[58:59]
	v_pk_add_f32 v[26:27], v[26:27], v[74:75]
	v_pk_add_f32 v[24:25], v[24:25], v[72:73]
	v_pk_add_f32 v[22:23], v[22:23], v[70:71]
	v_pk_add_f32 v[20:21], v[20:21], v[66:67]

; #define LAS __attribute__((address_space(3)))
; template <int KIND> DI void attn_unit(const Params& P, int b, int h, int qb, char* shm, float lam, bool dry = false) {
;     ...
;     if (KIND == 0) { cb = P.t5[15 * 4 + h] * LOG2E;
;         for (int i = tid; i < 2175; i += 512) { const int rel = i - 2111; const int n = rel < 0 ? -rel : rel;
;             int lg = 36 - __builtin_clz((unsigned)(n | 1)); lg = lg > 15 ? 15 : lg; int idx = n < 8 ? n : lg; idx += rel > 0 ? 16 : 0;
;             *(LAS float*)(shm3 + OFF_TAB + i * 4) = P.t5[idx * 4 + h] * LOG2E - cb; } }
;     if (KIND == 1) { cb = P.relb[h] * LOG2E;
;         if (tid < 255) { int idx = tid - 191; idx = idx < -128 ? -128 : idx; *(LAS float*)(shm3 + OFF_TAB + tid * 4) = P.relb[(idx + 128) * 8 + h] * LOG2E - cb; } }
;     const int NT = T_hi - T_lo + 1;
;     ...
;     ATT_DMA(ATT_TILE(0), 0);
;     if (NT > 1) ATT_DMA(ATT_TILE(1), SLOT);
;     if (NT > 2) ATT_DMA(ATT_TILE(2), 2 * SLOT);
.LBB0_378:
	s_lshl_b32 s13, s28, 2
	v_mov_b32_e32 v36, v236
	v_mov_b32_e32 v0, s13
	global_load_dword v5, v0, s[80:81] offset:240
	v_readfirstlane_b32 s12, v36
	v_mov_b32_e32 v6, v36
	v_subrev_u32_e32 v0, 0x83f, v6
	v_sub_u32_e32 v1, 0x83f, v6
	v_max_i32_e32 v0, v0, v1
	v_or_b32_e32 v1, 1, v0
	v_ffbh_u32_e32 v1, v1
	v_sub_u32_e32 v1, 36, v1
	v_min_u32_e32 v1, 15, v1
	v_cmp_gt_i32_e32 vcc, 8, v0
	v_cmp_lt_i32_e64 s[4:5], s89, v6
	s_nop 0
	v_cndmask_b32_e32 v0, v1, v0, vcc
	v_cndmask_b32_e64 v1, 0, 16, s[4:5]
	v_add_u32_e32 v0, v0, v1
	v_lshl_add_u32 v0, v0, 2, s28
	v_lshlrev_b32_e32 v11, 2, v0
	global_load_dword v16, v11, s[80:81]
	v_add_u32_e32 v7, 512, v36
	v_subrev_u32_e32 v0, 0x83f, v7
	v_sub_u32_e32 v1, 0x83f, v7
	v_max_i32_e32 v0, v0, v1
	v_or_b32_e32 v1, 1, v0
	v_ffbh_u32_e32 v1, v1
	v_sub_u32_e32 v1, 36, v1
	v_min_u32_e32 v1, 15, v1
	v_cmp_gt_i32_e32 vcc, 8, v0
	v_cmp_lt_i32_e64 s[4:5], s89, v7
	s_nop 0
	v_cndmask_b32_e32 v0, v1, v0, vcc
	v_cndmask_b32_e64 v1, 0, 16, s[4:5]
	v_add_u32_e32 v0, v0, v1
	v_lshl_add_u32 v0, v0, 2, s28
	v_lshlrev_b32_e32 v12, 2, v0
	global_load_dword v17, v12, s[80:81]
	v_add_u32_e32 v8, 1024, v36
	v_subrev_u32_e32 v0, 0x83f, v8
	v_sub_u32_e32 v1, 0x83f, v8
	v_max_i32_e32 v0, v0, v1
	v_or_b32_e32 v1, 1, v0
	v_ffbh_u32_e32 v1, v1
	v_sub_u32_e32 v1, 36, v1
	v_min_u32_e32 v1, 15, v1
	v_cmp_gt_i32_e32 vcc, 8, v0
	v_cmp_lt_i32_e64 s[4:5], s89, v8
	s_nop 0
	v_cndmask_b32_e32 v0, v1, v0, vcc
	v_cndmask_b32_e64 v1, 0, 16, s[4:5]
	v_add_u32_e32 v0, v0, v1
	v_lshl_add_u32 v0, v0, 2, s28
	v_lshlrev_b32_e32 v13, 2, v0
	global_load_dword v18, v13, s[80:81]
	v_add_u32_e32 v9, 1536, v36
	v_subrev_u32_e32 v0, 0x83f, v9
	v_sub_u32_e32 v1, 0x83f, v9
	v_max_i32_e32 v0, v0, v1
	v_or_b32_e32 v1, 1, v0
	v_ffbh_u32_e32 v1, v1
	v_sub_u32_e32 v1, 36, v1
	v_min_u32_e32 v1, 15, v1
	v_cmp_gt_i32_e32 vcc, 8, v0
	v_cmp_lt_i32_e64 s[4:5], s89, v9
	s_nop 0
	v_cndmask_b32_e32 v0, v1, v0, vcc
	v_cndmask_b32_e64 v1, 0, 16, s[4:5]
	v_add_u32_e32 v0, v0, v1
	v_lshl_add_u32 v0, v0, 2, s28
	v_lshlrev_b32_e32 v14, 2, v0
	global_load_dword v19, v14, s[80:81]
	v_add_u32_e32 v10, 2048, v36
	v_subrev_u32_e32 v0, 0x83f, v10
	v_sub_u32_e32 v1, 0x83f, v10
	v_max_i32_e32 v0, v0, v1
	v_or_b32_e32 v1, 1, v0
	v_ffbh_u32_e32 v1, v1
	v_sub_u32_e32 v1, 36, v1
	v_min_u32_e32 v1, 15, v1
	v_cmp_gt_i32_e32 vcc, 8, v0
	v_cmp_lt_i32_e64 s[4:5], s89, v10
	s_nop 0
	v_cndmask_b32_e32 v0, v1, v0, vcc
	v_cndmask_b32_e64 v1, 0, 16, s[4:5]
	v_add_u32_e32 v0, v0, v1
	v_lshl_add_u32 v0, v0, 2, s28
	v_lshlrev_b32_e32 v15, 2, v0
	global_load_dword v20, v15, s[80:81]
	s_mov_b32 s4, 0x21000
	s_waitcnt vmcnt(0)
	v_mul_f32_e32 v4, 0x3fb8aa3b, v5
	v_fma_f32 v16, v16, s60, -v4
	v_lshl_add_u32 v0, v6, 2, s4
	ds_write_b32 v0, v16
	v_fma_f32 v17, v17, s60, -v4
	v_lshl_add_u32 v0, v7, 2, s4
	ds_write_b32 v0, v17
	v_fma_f32 v18, v18, s60, -v4
	v_lshl_add_u32 v0, v8, 2, s4
	ds_write_b32 v0, v18
	v_fma_f32 v19, v19, s60, -v4
	v_lshl_add_u32 v0, v9, 2, s4
	ds_write_b32 v0, v19
	v_cmp_gt_u32_e32 vcc, 0x7f, v36
	s_and_saveexec_b64 s[6:7], vcc
	v_fma_f32 v20, v20, s60, -v4
	v_lshl_add_u32 v0, v10, 2, s4
	ds_write_b32 v0, v20
	s_or_b64 exec, exec, s[6:7]
	s_lshl_b32 s0, s28, 21
	s_mul_i32 s1, s2, 0x1800000
	s_ashr_i32 s11, s12, 6
	s_add_i32 s0, s0, s1
	s_ashr_i32 s8, s12, 8
	s_and_b32 s9, s11, 3
	s_lshl_b32 s10, s0, 1
	s_add_u32 s4, s24, s10
	s_addc_u32 s5, s25, 0
	s_lshl_b32 s0, s11, 9
	s_ashr_i32 s1, s0, 31
	s_lshl_b64 s[0:1], s[0:1], 1
	v_and_b32_e32 v195, 63, v36
	s_add_u32 s4, s4, s0
	s_mul_i32 s2, s2, 48
	s_addc_u32 s5, s5, s1
	v_lshlrev_b32_e32 v190, 4, v195
	v_mov_b32_e32 v191, v2
	s_add_i32 s2, s13, s2
	v_lshl_add_u64 v[38:39], s[4:5], 0, v[190:191]
	s_add_i32 s4, s2, s8
	s_ashr_i32 s5, s4, 31
	s_lshl_b64 s[4:5], s[4:5], 20
	s_add_u32 s2, s26, s4
	s_addc_u32 s7, s27, s5
	s_lshl_b32 s6, s9, 10
	s_add_u32 s6, s2, s6
	s_addc_u32 s7, s7, 0
	s_lshl_b32 s11, s11, 10
	s_cmp_lg_u32 0, -1
	s_cselect_b32 s2, 0, 0
	v_lshl_add_u64 v[40:41], s[6:7], 0, v[190:191]
	s_add_i32 s2, s11, s2
	s_mov_b32 s6, m0
	s_mov_b32 m0, s2
	s_nop 0
	global_load_lds_dwordx4 v[38:39], off
	s_mov_b32 m0, s6
	v_lshl_add_u64 v[0:1], v[38:39], 0, s[94:95]
	s_add_i32 s6, s2, 0x2000
	s_mov_b32 s7, m0
	s_mov_b32 m0, s6
	s_nop 0
	global_load_lds_dwordx4 v[0:1], off
	s_mov_b32 m0, s7
	s_add_i32 s6, s2, 0x4000
	s_mov_b32 s7, m0
	s_mov_b32 m0, s6
	s_nop 0
	global_load_lds_dwordx4 v[40:41], off
	s_mov_b32 m0, s7
	v_lshl_add_u64 v[0:1], v[40:41], 0, s[94:95]
	s_add_i32 s6, s2, 0x6000
	s_mov_b32 s7, m0
	s_mov_b32 m0, s6
	s_nop 0
	global_load_lds_dwordx4 v[0:1], off
	s_mov_b32 m0, s7
	v_lshl_add_u64 v[0:1], v[38:39], 0, s[62:63]
	s_add_i32 s6, s2, 0x8400
	s_mov_b32 s7, m0
	s_mov_b32 m0, s6
	s_nop 0
	global_load_lds_dwordx4 v[0:1], off
	s_mov_b32 m0, s7
	v_lshl_add_u64 v[0:1], v[38:39], 0, s[54:55]
	s_add_i32 s6, s2, 0xa400
	s_mov_b32 s7, m0
	s_mov_b32 m0, s6
	s_nop 0
	global_load_lds_dwordx4 v[0:1], off
	s_mov_b32 m0, s7
	v_lshl_add_u64 v[0:1], v[40:41], 0, s[92:93]
	s_add_i32 s6, s2, 0xc400
	s_mov_b32 s7, m0
	s_mov_b32 m0, s6
	s_nop 0
	global_load_lds_dwordx4 v[0:1], off
	s_mov_b32 m0, s7
	s_mov_b64 s[6:7], 0x201000
	s_add_i32 s2, s2, 0xe400
	v_lshl_add_u64 v[0:1], v[40:41], 0, s[6:7]
	s_mov_b32 s6, m0
	s_mov_b32 m0, s2
	s_nop 0
	global_load_lds_dwordx4 v[0:1], off
	s_mov_b32 m0, s6
	s_cmp_lg_u32 s3, 0
	s_cselect_b64 s[6:7], -1, 0
	s_and_b64 vcc, exec, s[6:7]
	s_cbranch_vccz .LBB0_388
	s_cmp_lg_u32 0, -1
	s_cselect_b32 s2, 0, 0
	s_mov_b64 s[14:15], 0x4000
	s_add_i32 s2, s2, s11
	v_lshl_add_u64 v[0:1], v[38:39], 0, s[14:15]
	s_add_i32 s13, s2, 0x10800
	s_mov_b32 s14, m0
	s_mov_b32 m0, s13
	s_nop 0
	global_load_lds_dwordx4 v[0:1], off
	s_mov_b32 m0, s14
	s_mov_b64 s[14:15], 0x204000
	v_lshl_add_u64 v[0:1], v[38:39], 0, s[14:15]
	s_add_i32 s13, s2, 0x12800
	s_mov_b32 s14, m0
	s_mov_b32 m0, s13
	s_nop 0
	global_load_lds_dwordx4 v[0:1], off
	s_mov_b32 m0, s14
	v_lshl_add_u64 v[0:1], v[40:41], 0, s[62:63]
	s_add_i32 s13, s2, 0x14800
	s_mov_b32 s14, m0
	s_mov_b32 m0, s13
	s_nop 0
	global_load_lds_dwordx4 v[0:1], off
	s_mov_b32 m0, s14
	v_lshl_add_u64 v[0:1], v[40:41], 0, s[54:55]
	s_add_i32 s2, s2, 0x16800
	s_mov_b32 s13, m0
	s_mov_b32 m0, s2
	s_nop 0
	global_load_lds_dwordx4 v[0:1], off
	s_mov_b32 m0, s13
